# prologue de-serialisation: Q fragments of each attention pass prefetched straight into their registers (first pass at phase start, next pass at the previous epilogue start), k-norm weights loaded at p
# speedup vs baseline: 1.0172x; 1.0077x over previous
.LBB0_422:
	s_ashr_i32 s84, s9, 8
	s_ashr_i32 s85, s2, 2
	s_and_b32 s85, s85, -2
	s_add_i32 s84, s84, s85
	s_bfe_u32 s85, s9, 0x20006
	s_lshl_b32 s85, s85, 4
	v_or_b32_e32 v192, s85, v150
	v_readlane_b32 s60, v252, 2
	v_readlane_b32 s61, v252, 3
	s_nop 3
	s_and_b32 s62, s2, 7
	s_lshl_b32 s62, s62, 7
	s_add_u32 s60, s60, s62
	s_addc_u32 s61, s61, 0
	v_and_b32_e32 v194, 24, v152
	v_lshlrev_b32_e32 v194, 1, v194
	v_mov_b32_e32 v195, 0
	v_lshl_add_u64 v[194:195], s[60:61], 0, v[194:195]
	s_ashr_i32 s85, s84, 4
	s_mul_hi_i32 s89, s85, 0x1100
	s_mul_i32 s88, s85, 0x1100
	s_lshl_b32 s90, s84, 2
	s_and_b32 s90, s90, 60
	s_lshl_b32 s90, s90, 6
	s_mov_b32 s87, 0
	v_or_b32_e32 v188, s88, v192
	v_mov_b32_e32 v189, s89
	s_mov_b32 s86, s90
	v_lshl_add_u64 v[190:191], v[188:189], 0, s[86:87]
	v_lshlrev_b64 v[190:191], 10, v[190:191]
	v_lshl_add_u64 v[190:191], v[194:195], 0, v[190:191]
	global_load_dwordx4 v[132:135], v[190:191], off
	global_load_dwordx4 v[136:139], v[190:191], off offset:64
	s_or_b32 s86, s90, 0x40
	v_lshl_add_u64 v[190:191], v[188:189], 0, s[86:87]
	v_lshlrev_b64 v[190:191], 10, v[190:191]
	v_lshl_add_u64 v[190:191], v[194:195], 0, v[190:191]
	global_load_dwordx4 v[140:143], v[190:191], off
	global_load_dwordx4 v[144:147], v[190:191], off offset:64
	s_or_b32 s86, s90, 0x80
	v_lshl_add_u64 v[190:191], v[188:189], 0, s[86:87]
	v_lshlrev_b64 v[190:191], 10, v[190:191]
	v_lshl_add_u64 v[190:191], v[194:195], 0, v[190:191]
	global_load_dwordx4 v[196:199], v[190:191], off
	global_load_dwordx4 v[200:203], v[190:191], off offset:64
	s_or_b32 s86, s90, 0xc0
	v_lshl_add_u64 v[190:191], v[188:189], 0, s[86:87]
	v_lshlrev_b64 v[190:191], 10, v[190:191]
	v_lshl_add_u64 v[190:191], v[194:195], 0, v[190:191]
	global_load_dwordx4 v[156:159], v[190:191], off
	global_load_dwordx4 v[160:163], v[190:191], off offset:64
	v_lshlrev_b32_e32 v204, 2, v226
	global_load_dword v255, v204, s[24:25]
	v_cmp_eq_u32_e32 vcc, 0, v96
	s_waitcnt lgkmcnt(0)
	s_barrier
	s_and_saveexec_b64 s[0:1], vcc
	v_mov_b32_e32 v0, 0
	ds_write_b32 v0, v0 offset:30720
	s_or_b64 exec, exec, s[0:1]
	s_movk_i32 s0, 0x1e00
	v_cmp_gt_i32_e32 vcc, s0, v96
	s_waitcnt lgkmcnt(0)
	s_barrier
	s_and_saveexec_b64 s[0:1], vcc
	s_cbranch_execz .LBB0_427
	v_add_u32_e32 v0, 0xfffffe00, v96
	v_lshl_add_u32 v1, v96, 2, 0
	s_mov_b64 s[6:7], 0
	v_mov_b32_e32 v2, 0
	s_movk_i32 s4, 0x1bff

.LBB0_447:
	s_or_b64 exec, exec, s[0:1]
	v_lshlrev_b32_e32 v0, 2, v226
	s_waitcnt lgkmcnt(0)
	s_barrier
	v_mov_b32_e32 v0, v255
	s_waitcnt vmcnt(1)
	v_mbcnt_hi_u32_b32 v1, -1, v154
	v_and_b32_e32 v2, 64, v1
	v_xor_b32_e32 v3, 1, v1
	v_add_u32_e32 v2, 64, v2
	v_cmp_lt_i32_e32 vcc, v3, v2
	v_xor_b32_e32 v4, 2, v1
	v_xor_b32_e32 v5, 4, v1
	v_cndmask_b32_e32 v3, v1, v3, vcc
	v_lshlrev_b32_e32 v3, 2, v3
	v_cmp_lt_i32_e32 vcc, v4, v2
	v_xor_b32_e32 v6, 8, v1
	s_ashr_i32 s0, s2, 2
	v_cndmask_b32_e32 v4, v1, v4, vcc
	v_lshlrev_b32_e32 v4, 2, v4
	v_cmp_lt_i32_e32 vcc, v5, v2
	s_ashr_i32 s65, s9, 8
	s_and_b32 s0, s0, -2
	v_cndmask_b32_e32 v5, v1, v5, vcc
	v_lshlrev_b32_e32 v5, 2, v5
	v_cmp_lt_i32_e32 vcc, v6, v2
	s_add_i32 s65, s65, s0
	s_ashr_i32 s0, s65, 1
	v_cndmask_b32_e32 v6, v1, v6, vcc
	v_lshlrev_b32_e32 v6, 2, v6
	s_and_b32 s64, s2, 7
	s_and_b32 s0, s0, -8
	s_or_b32 s0, s0, s64
	s_cmp_gt_i32 s0, 63
	s_mov_b32 s37, 0
	s_waitcnt vmcnt(0)
	v_and_b32_e32 v7, 0x7fffffff, v0
	ds_bpermute_b32 v3, v3, v7
	v_max_f32_e64 v0, |v0|, |v0|
	s_waitcnt lgkmcnt(0)
	v_max_f32_e32 v3, v3, v3
	v_max_f32_e32 v0, v0, v3
	ds_bpermute_b32 v3, v4, v0
	v_xor_b32_e32 v4, 16, v1
	v_cmp_lt_i32_e32 vcc, v4, v2
	s_waitcnt lgkmcnt(0)
	v_max_f32_e32 v3, v3, v3
	v_max_f32_e32 v0, v0, v3
	ds_bpermute_b32 v3, v5, v0
	v_cndmask_b32_e32 v4, v1, v4, vcc
	v_lshlrev_b32_e32 v4, 2, v4
	v_xor_b32_e32 v5, 32, v1
	v_cmp_lt_i32_e32 vcc, v5, v2
	s_waitcnt lgkmcnt(0)
	v_max_f32_e32 v3, v3, v3
	v_max_f32_e32 v0, v0, v3
	ds_bpermute_b32 v3, v6, v0
	v_cndmask_b32_e32 v1, v1, v5, vcc
	v_lshlrev_b32_e32 v1, 2, v1
	s_waitcnt lgkmcnt(0)
	v_max_f32_e32 v3, v3, v3
	v_max_f32_e32 v0, v0, v3
	ds_bpermute_b32 v3, v4, v0
	s_waitcnt lgkmcnt(0)
	v_max_f32_e32 v2, v3, v3
	v_max_f32_e32 v0, v0, v2
	ds_bpermute_b32 v1, v1, v0
	s_cbranch_scc1 .LBB0_547
	v_readlane_b32 s12, v252, 0
	v_readlane_b32 s13, v252, 1
	v_readlane_b32 s14, v252, 2
	v_readlane_b32 s15, v252, 3
	v_readlane_b32 s16, v252, 4
	v_readlane_b32 s17, v252, 5
	s_add_i32 s0, s3, 7
	v_readlane_b32 s18, v252, 6
	v_readlane_b32 s19, v252, 7
	s_mov_b64 s[10:11], s[14:15]
	s_mov_b64 s[12:13], s[16:17]
	s_ashr_i32 s0, s0, 2
	s_and_b32 s25, s13, 0xffff
	s_and_b32 s41, s77, 0xffff
	s_and_b32 s66, s0, -2
	s_bfe_u32 s67, s9, 0x20006
	s_cmp_eq_u32 s67, 2
	s_mov_b64 s[28:29], s[68:69]
	s_cselect_b32 s68, 24, 32
	s_lshl_b32 s69, s67, 4
	s_waitcnt lgkmcnt(0)
	v_max_f32_e32 v1, v1, v1
	v_max_f32_e32 v0, v0, v0
	v_or_b32_e32 v216, s69, v150
	v_max_f32_e32 v0, v0, v1
	v_sub_u32_e64 v1, v216, 8 clamp
	v_min_u32_e32 v229, 48, v1
	s_lshl_b32 s0, s8, 13
	v_lshlrev_b32_e32 v1, 1, v226
	s_add_i32 s0, s0, 0
	s_lshl_b32 s72, s64, 6
	v_and_or_b32 v1, v1, 24, v151
	s_lshl_b32 s5, s64, 7
	v_lshl_add_u32 v230, v226, 4, s0
	v_and_b32_e32 v232, 24, v152
	v_lshl_or_b32 v233, v1, 10, v153
	v_lshlrev_b32_e32 v253, 1, v226
	v_and_b32_e32 v253, 24, v253
	v_lshrrev_b32_e32 v254, 4, v226
	v_or_b32_e32 v253, v253, v254
	v_and_b32_e32 v254, 3, v226
	v_lshlrev_b32_e32 v254, 4, v254
	v_lshl_or_b32 v233, v253, 10, v254
	v_mul_u32_u24_e32 v1, 0x1100, v1
	s_add_u32 s0, s10, s5
	v_mul_f32_e32 v0, 0x41000000, v0
	s_mov_b64 s[14:15], s[18:19]
	v_or_b32_e32 v1, v1, v232
	s_addc_u32 s1, s11, 0
	v_mul_f32_e32 v227, 0x3f8020c5, v0
	v_mov_b32_e32 v0, 0
	v_lshlrev_b32_e32 v234, 1, v1
	s_add_u32 s46, s14, s5
	v_lshlrev_b32_e32 v1, 1, v96
	s_mul_i32 s4, s64, 0xf00
	v_lshlrev_b32_e32 v2, 1, v232
	v_mov_b32_e32 v3, v0
	s_addc_u32 s47, s15, 0
	v_and_b32_e32 v1, 0x60, v1
	ds_read_b32 v228, v0 offset:30720
	v_lshl_add_u64 v[218:219], s[0:1], 0, v[2:3]
	s_add_u32 s48, s78, s5
	v_or_b32_e32 v1, s4, v1
	v_lshlrev_b32_e32 v2, 2, v150
	s_addc_u32 s49, s79, 0
	v_sub_u32_e32 v1, v1, v2
	s_lshl_b32 s0, s67, 6
	v_subrev_u32_e32 v1, s0, v1
	v_add_u32_e32 v1, 0, v1
	s_mov_b32 s27, 0x20000
	s_mov_b32 s26, 0x2200000
	s_mov_b32 s24, s12
	s_mov_b32 s40, s76
	v_add_u32_e32 v231, 0x8000, v230
	v_or_b32_e32 v235, 64, v233
	v_add_u32_e32 v236, 0x7c, v1
	s_mov_b32 s70, 0xf800000
	v_mov_b32_e32 v237, 0x260
	v_mov_b32_e32 v238, 0xf149f2ca
	v_mov_b32_e32 v148, v196
	v_mov_b32_e32 v149, v197
	v_mov_b32_e32 v150, v198
	v_mov_b32_e32 v151, v199
	v_mov_b32_e32 v152, v200
	v_mov_b32_e32 v153, v201
	v_mov_b32_e32 v154, v202
	v_mov_b32_e32 v155, v203
	s_mov_b32 s4, s65
	s_mov_b32 s71, 0
	s_branch .LBB0_451

.LBB0_450:
	s_add_i32 s84, s71, 1
	s_mul_i32 s84, s84, s66
	s_add_i32 s84, s84, s65
	s_ashr_i32 s85, s84, 1
	s_and_b32 s85, s85, -8
	s_or_b32 s85, s85, s64
	s_cmp_gt_i32 s85, 63
	s_cbranch_scc1 .Latt_qpf_skip
	s_ashr_i32 s85, s84, 4
	s_mul_hi_i32 s89, s85, 0x1100
	s_mul_i32 s88, s85, 0x1100
	s_lshl_b32 s90, s84, 2
	s_and_b32 s90, s90, 60
	s_lshl_b32 s90, s90, 6
	s_mov_b32 s87, 0
	v_or_b32_e32 v188, s88, v216
	v_mov_b32_e32 v189, s89
	s_mov_b32 s86, s90
	v_lshl_add_u64 v[190:191], v[188:189], 0, s[86:87]
	v_lshlrev_b64 v[190:191], 10, v[190:191]
	v_lshl_add_u64 v[190:191], v[218:219], 0, v[190:191]
	global_load_dwordx4 v[132:135], v[190:191], off
	global_load_dwordx4 v[136:139], v[190:191], off offset:64
	s_or_b32 s86, s90, 0x40
	v_lshl_add_u64 v[190:191], v[188:189], 0, s[86:87]
	v_lshlrev_b64 v[190:191], 10, v[190:191]
	v_lshl_add_u64 v[190:191], v[218:219], 0, v[190:191]
	global_load_dwordx4 v[140:143], v[190:191], off
	global_load_dwordx4 v[144:147], v[190:191], off offset:64
	s_or_b32 s86, s90, 0x80
	v_lshl_add_u64 v[190:191], v[188:189], 0, s[86:87]
	v_lshlrev_b64 v[190:191], 10, v[190:191]
	v_lshl_add_u64 v[190:191], v[218:219], 0, v[190:191]
	global_load_dwordx4 v[148:151], v[190:191], off
	global_load_dwordx4 v[152:155], v[190:191], off offset:64
	s_or_b32 s86, s90, 0xc0
	v_lshl_add_u64 v[190:191], v[188:189], 0, s[86:87]
	v_lshlrev_b64 v[190:191], 10, v[190:191]
	v_lshl_add_u64 v[190:191], v[218:219], 0, v[190:191]
	global_load_dwordx4 v[156:159], v[190:191], off
	global_load_dwordx4 v[160:163], v[190:191], off offset:64
.Latt_qpf_skip:
	v_mov_b32_e32 v1, v226
	v_mov_b32_e32 v3, s73
	v_and_or_b32 v8, v1, 15, s69
	v_ashrrev_i32_e32 v1, 1, v1
	v_and_b32_e32 v4, -8, v1
	v_or_b32_e32 v2, s74, v8
	v_ashrrev_i32_e32 v5, 31, v4
	v_lshlrev_b64 v[18:19], 1, v[4:5]
	v_lshl_add_u64 v[6:7], v[2:3], 0, s[36:37]
	v_lshl_add_u64 v[4:5], s[46:47], 0, v[18:19]
	v_lshlrev_b64 v[6:7], 10, v[6:7]
	v_lshl_add_u64 v[6:7], v[4:5], 0, v[6:7]
	v_mov_b32_e32 v1, v222
	s_ashr_i32 s59, s58, 31
	s_nop 0
	v_permlane16_swap_b32_e32 v222, v1
	s_lshl_b64 s[0:1], s[58:59], 12
	v_add_f32_e32 v1, v222, v1
	v_or_b32_e32 v40, s0, v8
	v_mov_b32_e32 v10, v1
	v_mov_b32_e32 v21, s1
	v_lshl_add_u64 v[6:7], v[2:3], 0, s[54:55]
	v_lshl_add_u64 v[8:9], v[2:3], 0, s[50:51]
	v_lshl_add_u64 v[2:3], v[2:3], 0, s[56:57]
	v_permlane32_swap_b32_e32 v1, v10
	v_or_b32_e32 v20, s36, v40
	v_lshlrev_b64 v[6:7], 10, v[6:7]
	v_lshlrev_b64 v[8:9], 10, v[8:9]
	v_lshlrev_b64 v[2:3], 10, v[2:3]
	v_add_f32_e32 v1, v1, v10
	v_lshlrev_b64 v[10:11], 11, v[20:21]
	v_lshl_add_u64 v[10:11], s[48:49], 0, v[10:11]
	v_lshl_add_u64 v[6:7], v[4:5], 0, v[6:7]
	v_lshl_add_u64 v[8:9], v[4:5], 0, v[8:9]
	v_lshl_add_u64 v[2:3], v[4:5], 0, v[2:3]
	v_lshl_add_u64 v[38:39], v[10:11], 0, v[18:19]
	s_nop 0
	s_nop 0
	v_mov_b32_e32 v22, v204
	v_mov_b32_e32 v23, v205
	v_mov_b32_e32 v24, v206
	v_mov_b32_e32 v25, v207
	v_mov_b32_e32 v26, v208
	v_mov_b32_e32 v27, v209
	v_mov_b32_e32 v28, v210
	v_mov_b32_e32 v29, v211
	v_mov_b32_e32 v30, v212
	v_mov_b32_e32 v31, v213
	v_mov_b32_e32 v32, v214
	v_mov_b32_e32 v33, v215
	v_mov_b32_e32 v34, v242
	v_mov_b32_e32 v35, v243
	v_mov_b32_e32 v36, v244
	v_mov_b32_e32 v37, v245
	v_mov_b32_e32 v14, v180
	v_mov_b32_e32 v15, v181
	v_mov_b32_e32 v16, v182
	v_mov_b32_e32 v17, v183
	v_mov_b32_e32 v10, v184
	v_mov_b32_e32 v11, v185
	v_mov_b32_e32 v12, v186
	v_mov_b32_e32 v13, v187
	v_mov_b32_e32 v6, v80
	v_mov_b32_e32 v7, v81
	v_mov_b32_e32 v8, v82
	v_mov_b32_e32 v9, v83
	v_mov_b32_e32 v2, v84
	v_mov_b32_e32 v3, v85
	v_mov_b32_e32 v4, v86
	v_mov_b32_e32 v5, v87
	v_div_scale_f32 v20, s[0:1], v1, v1, 1.0
	v_rcp_f32_e32 v42, v20
	v_div_scale_f32 v41, vcc, 1.0, v1, 1.0
	s_add_i32 s71, s71, 1
	v_fma_f32 v43, -v20, v42, 1.0
	v_fmac_f32_e32 v42, v43, v42
	v_mul_f32_e32 v43, v41, v42
	v_fma_f32 v44, -v20, v43, v41
	v_fmac_f32_e32 v43, v44, v42
	v_fma_f32 v20, -v20, v43, v41
	v_div_fmas_f32 v20, v20, v42, v43
	v_div_fixup_f32 v1, v20, v1, 1.0
	v_mul_f32_e32 v20, v96, v1
	v_mul_f32_e32 v41, v97, v1
	v_mul_f32_e32 v43, v99, v1
	v_mul_f32_e32 v42, v98, v1
	v_mul_f32_e32 v45, v89, v1
	v_mul_f32_e32 v47, v91, v1
	v_mul_f32_e32 v48, v72, v1
	v_mul_f32_e32 v49, v73, v1
	v_mul_f32_e32 v44, v88, v1
	v_mul_f32_e32 v46, v90, v1
	v_lshlrev_b32_e32 v50, 16, v22
	v_and_b32_e32 v22, 0xffff0000, v22
	v_lshlrev_b32_e32 v51, 16, v23
	v_and_b32_e32 v23, 0xffff0000, v23
	v_mul_f32_e32 v20, v20, v50
	v_mul_f32_e32 v22, v41, v22
	v_lshlrev_b32_e32 v72, 16, v24
	v_and_b32_e32 v24, 0xffff0000, v24
	v_lshlrev_b32_e32 v73, 16, v25
	v_and_b32_e32 v25, 0xffff0000, v25
	v_lshlrev_b32_e32 v76, 16, v26
	v_mul_f32_e32 v23, v43, v23
	v_cvt_pk_bf16_f32 v22, v20, v22
	v_and_b32_e32 v20, 0xffff0000, v26
	v_mov_b32_e32 v26, v223
	v_mul_f32_e32 v41, v42, v51
	v_mul_f32_e32 v24, v45, v24
	v_mul_f32_e32 v25, v47, v25
	v_cvt_pk_bf16_f32 v23, v41, v23
	v_mul_f32_e32 v20, v49, v20
	v_permlane16_swap_b32_e32 v223, v26
	v_mul_f32_e32 v42, v44, v72
	v_mul_f32_e32 v43, v46, v73
	v_mul_f32_e32 v44, v48, v76
	v_cvt_pk_bf16_f32 v24, v42, v24
	v_cvt_pk_bf16_f32 v25, v43, v25
	global_store_dwordx4 v[38:39], v[22:25], off offset:1024
	v_add_f32_e32 v26, v223, v26
	s_nop 0
	v_cvt_pk_bf16_f32 v22, v44, v20
	v_mul_f32_e32 v20, v74, v1
	v_lshlrev_b32_e32 v23, 16, v27
	v_mul_f32_e32 v20, v20, v23
	v_mul_f32_e32 v23, v75, v1
	v_and_b32_e32 v24, 0xffff0000, v27
	v_mov_b32_e32 v27, v26
	v_mul_f32_e32 v23, v23, v24
	s_nop 0
	v_permlane32_swap_b32_e32 v26, v27
	v_cvt_pk_bf16_f32 v23, v20, v23
	v_mul_f32_e32 v20, v68, v1
	v_lshlrev_b32_e32 v24, 16, v28
	v_add_f32_e32 v26, v26, v27
	v_mul_f32_e32 v20, v20, v24
	v_mul_f32_e32 v24, v69, v1
	v_and_b32_e32 v25, 0xffff0000, v28
	v_div_scale_f32 v27, s[0:1], v26, v26, 1.0
	v_mul_f32_e32 v24, v24, v25
	v_rcp_f32_e32 v28, v27
	v_cvt_pk_bf16_f32 v24, v20, v24
	v_mul_f32_e32 v20, v70, v1
	v_lshlrev_b32_e32 v25, 16, v29
	v_mul_f32_e32 v20, v20, v25
	v_mul_f32_e32 v1, v71, v1
	v_and_b32_e32 v25, 0xffff0000, v29
	v_mul_f32_e32 v1, v1, v25
	v_cvt_pk_bf16_f32 v25, v20, v1
	v_fma_f32 v1, -v27, v28, 1.0
	v_fmac_f32_e32 v28, v1, v28
	v_div_scale_f32 v1, vcc, 1.0, v26, 1.0
	v_mul_f32_e32 v20, v1, v28
	global_store_dwordx4 v[38:39], v[22:25], off offset:1088
	s_nop 1
	v_fma_f32 v22, -v27, v20, v1
	v_fmac_f32_e32 v20, v22, v28
	v_fma_f32 v1, -v27, v20, v1
	v_div_fmas_f32 v1, v1, v28, v20
	v_or_b32_e32 v20, s54, v40
	v_lshlrev_b64 v[22:23], 11, v[20:21]
	v_div_fixup_f32 v1, v1, v26, 1.0
	v_lshl_add_u64 v[22:23], s[48:49], 0, v[22:23]
	v_lshl_add_u64 v[26:27], v[22:23], 0, v[18:19]
	v_mul_f32_e32 v20, v64, v1
	v_lshlrev_b32_e32 v22, 16, v30
	v_mul_f32_e32 v20, v20, v22
	v_mul_f32_e32 v22, v65, v1
	v_and_b32_e32 v23, 0xffff0000, v30
	v_mul_f32_e32 v22, v22, v23
	v_cvt_pk_bf16_f32 v22, v20, v22
	v_mul_f32_e32 v20, v66, v1
	v_lshlrev_b32_e32 v23, 16, v31
	v_mul_f32_e32 v20, v20, v23
	v_mul_f32_e32 v23, v67, v1
	v_and_b32_e32 v24, 0xffff0000, v31
	v_mul_f32_e32 v23, v23, v24
	v_cvt_pk_bf16_f32 v23, v20, v23
	v_mul_f32_e32 v20, v60, v1
	v_lshlrev_b32_e32 v24, 16, v32
	v_mul_f32_e32 v20, v20, v24
	v_mul_f32_e32 v24, v61, v1
	v_and_b32_e32 v25, 0xffff0000, v32
	v_mul_f32_e32 v24, v24, v25
	v_cvt_pk_bf16_f32 v24, v20, v24
	v_mul_f32_e32 v20, v62, v1
	v_lshlrev_b32_e32 v25, 16, v33
	v_mul_f32_e32 v20, v20, v25
	v_mul_f32_e32 v25, v63, v1
	v_and_b32_e32 v28, 0xffff0000, v33
	v_mul_f32_e32 v25, v25, v28
	v_cvt_pk_bf16_f32 v25, v20, v25
	global_store_dwordx4 v[26:27], v[22:25], off offset:1024
	v_mul_f32_e32 v20, v56, v1
	v_mov_b32_e32 v28, v224
	v_lshlrev_b32_e32 v22, 16, v34
	v_mul_f32_e32 v20, v20, v22
	v_mul_f32_e32 v22, v57, v1
	v_and_b32_e32 v23, 0xffff0000, v34
	v_mul_f32_e32 v22, v22, v23
	v_permlane16_swap_b32_e32 v224, v28
	v_cvt_pk_bf16_f32 v22, v20, v22
	v_mul_f32_e32 v20, v58, v1
	v_lshlrev_b32_e32 v23, 16, v35
	v_add_f32_e32 v28, v224, v28
	v_mul_f32_e32 v20, v20, v23
	v_mul_f32_e32 v23, v59, v1
	v_and_b32_e32 v24, 0xffff0000, v35
	v_mov_b32_e32 v29, v28
	v_mul_f32_e32 v23, v23, v24
	s_nop 0
	v_permlane32_swap_b32_e32 v28, v29
	v_cvt_pk_bf16_f32 v23, v20, v23
	v_mul_f32_e32 v20, v52, v1
	v_lshlrev_b32_e32 v24, 16, v36
	v_add_f32_e32 v28, v28, v29
	v_mul_f32_e32 v20, v20, v24
	v_mul_f32_e32 v24, v53, v1
	v_and_b32_e32 v25, 0xffff0000, v36
	v_div_scale_f32 v29, s[0:1], v28, v28, 1.0
	v_mul_f32_e32 v24, v24, v25
	v_rcp_f32_e32 v30, v29
	v_cvt_pk_bf16_f32 v24, v20, v24
	v_mul_f32_e32 v20, v54, v1
	v_lshlrev_b32_e32 v25, 16, v37
	v_mul_f32_e32 v20, v20, v25
	v_mul_f32_e32 v1, v55, v1
	v_and_b32_e32 v25, 0xffff0000, v37
	v_mul_f32_e32 v1, v1, v25
	v_cvt_pk_bf16_f32 v25, v20, v1
	v_fma_f32 v1, -v29, v30, 1.0
	v_fmac_f32_e32 v30, v1, v30
	v_div_scale_f32 v1, vcc, 1.0, v28, 1.0
	v_mul_f32_e32 v20, v1, v30
	global_store_dwordx4 v[26:27], v[22:25], off offset:1088
	s_nop 1
	v_fma_f32 v22, -v29, v20, v1
	v_fmac_f32_e32 v20, v22, v30
	v_fma_f32 v1, -v29, v20, v1
	v_div_fmas_f32 v1, v1, v30, v20
	v_div_fixup_f32 v1, v1, v28, 1.0
	v_or_b32_e32 v20, s50, v40
	v_lshlrev_b64 v[22:23], 11, v[20:21]
	v_mul_f32_e32 v20, v128, v1
	v_lshlrev_b32_e32 v24, 16, v14
	v_mul_f32_e32 v20, v20, v24
	v_mul_f32_e32 v24, v129, v1
	v_and_b32_e32 v14, 0xffff0000, v14
	v_mul_f32_e32 v14, v24, v14
	v_cvt_pk_bf16_f32 v14, v20, v14
	v_mul_f32_e32 v20, v130, v1
	v_lshlrev_b32_e32 v24, 16, v15
	v_mul_f32_e32 v20, v20, v24
	v_mul_f32_e32 v24, v131, v1
	v_and_b32_e32 v15, 0xffff0000, v15
	v_mul_f32_e32 v15, v24, v15
	v_cvt_pk_bf16_f32 v15, v20, v15
	v_mul_f32_e32 v20, v124, v1
	v_lshlrev_b32_e32 v24, 16, v16
	v_mul_f32_e32 v20, v20, v24
	v_mul_f32_e32 v24, v125, v1
	v_and_b32_e32 v16, 0xffff0000, v16
	v_mul_f32_e32 v16, v24, v16
	v_cvt_pk_bf16_f32 v16, v20, v16
	v_mul_f32_e32 v20, v126, v1
	v_lshlrev_b32_e32 v24, 16, v17
	v_lshl_add_u64 v[22:23], s[48:49], 0, v[22:23]
	v_mul_f32_e32 v20, v20, v24
	v_mul_f32_e32 v24, v127, v1
	v_and_b32_e32 v17, 0xffff0000, v17
	v_lshl_add_u64 v[22:23], v[22:23], 0, v[18:19]
	v_mul_f32_e32 v17, v24, v17
	v_cvt_pk_bf16_f32 v17, v20, v17
	global_store_dwordx4 v[22:23], v[14:17], off offset:1024
	v_or_b32_e32 v20, s56, v40
	s_nop 0
	v_mul_f32_e32 v14, v120, v1
	v_lshlrev_b32_e32 v15, 16, v10
	v_mul_f32_e32 v14, v14, v15
	v_mul_f32_e32 v15, v121, v1
	v_and_b32_e32 v10, 0xffff0000, v10
	v_mul_f32_e32 v10, v15, v10
	v_cvt_pk_bf16_f32 v10, v14, v10
	v_mul_f32_e32 v14, v122, v1
	v_lshlrev_b32_e32 v15, 16, v11
	v_mul_f32_e32 v14, v14, v15
	v_mul_f32_e32 v15, v123, v1
	v_and_b32_e32 v11, 0xffff0000, v11
	v_mul_f32_e32 v11, v15, v11
	v_cvt_pk_bf16_f32 v11, v14, v11
	v_mul_f32_e32 v14, v116, v1
	v_lshlrev_b32_e32 v15, 16, v12
	v_mul_f32_e32 v14, v14, v15
	v_mul_f32_e32 v15, v117, v1
	v_and_b32_e32 v12, 0xffff0000, v12
	v_mul_f32_e32 v12, v15, v12
	v_cvt_pk_bf16_f32 v12, v14, v12
	v_mul_f32_e32 v14, v118, v1
	v_lshlrev_b32_e32 v15, 16, v13
	v_mul_f32_e32 v14, v14, v15
	v_mov_b32_e32 v15, v225
	s_nop 1
	v_permlane16_swap_b32_e32 v225, v15
	v_add_f32_e32 v15, v225, v15
	v_mov_b32_e32 v16, v15
	s_nop 1
	v_permlane32_swap_b32_e32 v15, v16
	v_add_f32_e32 v15, v15, v16
	v_div_scale_f32 v16, s[0:1], v15, v15, 1.0
	v_rcp_f32_e32 v17, v16
	v_mul_f32_e32 v1, v119, v1
	v_and_b32_e32 v13, 0xffff0000, v13
	v_mul_f32_e32 v1, v1, v13
	v_cvt_pk_bf16_f32 v13, v14, v1
	v_fma_f32 v1, -v16, v17, 1.0
	v_fmac_f32_e32 v17, v1, v17
	v_div_scale_f32 v1, vcc, 1.0, v15, 1.0
	global_store_dwordx4 v[22:23], v[10:13], off offset:1088
	s_mul_i32 s0, s71, s66
	s_add_i32 s4, s0, s65
	v_mul_f32_e32 v10, v1, v17
	v_fma_f32 v11, -v16, v10, v1
	v_fmac_f32_e32 v10, v11, v17
	v_fma_f32 v1, -v16, v10, v1
	v_div_fmas_f32 v1, v1, v17, v10
	v_div_fixup_f32 v1, v1, v15, 1.0
	v_mul_f32_e32 v12, v112, v1
	v_lshlrev_b32_e32 v13, 16, v6
	v_mul_f32_e32 v12, v12, v13
	v_mul_f32_e32 v13, v113, v1
	v_and_b32_e32 v6, 0xffff0000, v6
	v_mul_f32_e32 v6, v13, v6
	v_cvt_pk_bf16_f32 v6, v12, v6
	v_mul_f32_e32 v12, v114, v1
	v_lshlrev_b32_e32 v13, 16, v7
	v_mul_f32_e32 v12, v12, v13
	v_mul_f32_e32 v13, v115, v1
	v_and_b32_e32 v7, 0xffff0000, v7
	v_mul_f32_e32 v7, v13, v7
	v_cvt_pk_bf16_f32 v7, v12, v7
	v_mul_f32_e32 v12, v108, v1
	v_lshlrev_b32_e32 v13, 16, v8
	v_mul_f32_e32 v12, v12, v13
	v_mul_f32_e32 v13, v109, v1
	v_and_b32_e32 v8, 0xffff0000, v8
	v_mul_f32_e32 v8, v13, v8
	v_lshlrev_b64 v[10:11], 11, v[20:21]
	v_cvt_pk_bf16_f32 v8, v12, v8
	v_mul_f32_e32 v12, v110, v1
	v_lshlrev_b32_e32 v13, 16, v9
	v_lshl_add_u64 v[10:11], s[48:49], 0, v[10:11]
	v_mul_f32_e32 v12, v12, v13
	v_mul_f32_e32 v13, v111, v1
	v_and_b32_e32 v9, 0xffff0000, v9
	v_lshl_add_u64 v[10:11], v[10:11], 0, v[18:19]
	v_mul_f32_e32 v9, v13, v9
	v_cvt_pk_bf16_f32 v9, v12, v9
	global_store_dwordx4 v[10:11], v[6:9], off offset:1024
	s_ashr_i32 s0, s4, 1
	s_and_b32 s0, s0, -8
	v_mul_f32_e32 v6, v104, v1
	v_lshlrev_b32_e32 v7, 16, v2
	v_mul_f32_e32 v6, v6, v7
	v_mul_f32_e32 v7, v105, v1
	v_and_b32_e32 v2, 0xffff0000, v2
	v_mul_f32_e32 v2, v7, v2
	v_cvt_pk_bf16_f32 v2, v6, v2
	v_mul_f32_e32 v6, v106, v1
	v_lshlrev_b32_e32 v7, 16, v3
	v_mul_f32_e32 v6, v6, v7
	v_mul_f32_e32 v7, v107, v1
	v_and_b32_e32 v3, 0xffff0000, v3
	v_mul_f32_e32 v3, v7, v3
	v_cvt_pk_bf16_f32 v3, v6, v3
	v_mul_f32_e32 v6, v100, v1
	v_lshlrev_b32_e32 v7, 16, v4
	v_mul_f32_e32 v6, v6, v7
	v_mul_f32_e32 v7, v101, v1
	v_and_b32_e32 v4, 0xffff0000, v4
	v_mul_f32_e32 v4, v7, v4
	s_or_b32 s0, s0, s64
	v_cvt_pk_bf16_f32 v4, v6, v4
	v_mul_f32_e32 v6, v102, v1
	v_lshlrev_b32_e32 v7, 16, v5
	v_mul_f32_e32 v1, v103, v1
	v_and_b32_e32 v5, 0xffff0000, v5
	s_cmp_gt_i32 s0, 63
	v_mul_f32_e32 v6, v6, v7
	v_mul_f32_e32 v1, v1, v5
	v_cvt_pk_bf16_f32 v5, v6, v1
	global_store_dwordx4 v[10:11], v[2:5], off offset:1088
	s_cbranch_scc1 .LBB0_546

.LBB0_456:
	s_ashr_i32 s58, s4, 4
	s_lshl_b32 s0, s4, 2
	s_mul_hi_i32 s73, s58, 0x1100
	s_mul_i32 s74, s58, 0x1100
	s_and_b32 s5, s0, 60
	v_mov_b32_e32 v3, s73
	v_or_b32_e32 v2, s74, v216
	s_lshl_b32 s36, s5, 6
	v_lshl_add_u64 v[4:5], v[2:3], 0, s[36:37]
	v_lshlrev_b64 v[4:5], 10, v[4:5]
	v_lshl_add_u64 v[12:13], v[218:219], 0, v[4:5]
	s_mov_b32 s55, s37
	s_or_b32 s54, s36, 64
	s_waitcnt vmcnt(8)
	v_mov_b32_e32 v4, v132
	v_mov_b32_e32 v5, v133
	v_mov_b32_e32 v6, v134
	v_mov_b32_e32 v7, v135
	v_mov_b32_e32 v8, v136
	v_mov_b32_e32 v9, v137
	v_mov_b32_e32 v10, v138
	v_mov_b32_e32 v11, v139
	v_lshl_add_u64 v[12:13], v[2:3], 0, s[54:55]
	v_lshlrev_b64 v[12:13], 10, v[12:13]
	v_lshl_add_u64 v[20:21], v[218:219], 0, v[12:13]
	v_mov_b32_e32 v12, v140
	v_mov_b32_e32 v13, v141
	v_mov_b32_e32 v14, v142
	v_mov_b32_e32 v15, v143
	v_mov_b32_e32 v16, v144
	v_mov_b32_e32 v17, v145
	v_mov_b32_e32 v18, v146
	v_mov_b32_e32 v19, v147
	s_mov_b32 s51, s37
	s_or_b32 s50, s36, 0x80
	v_lshl_add_u64 v[20:21], v[2:3], 0, s[50:51]
	v_lshlrev_b64 v[20:21], 10, v[20:21]
	v_lshl_add_u64 v[24:25], v[218:219], 0, v[20:21]
	v_mov_b32_e32 v20, v148
	v_mov_b32_e32 v21, v149
	v_mov_b32_e32 v22, v150
	v_mov_b32_e32 v23, v151
	s_nop 0
	v_mov_b32_e32 v24, v152
	v_mov_b32_e32 v25, v153
	v_mov_b32_e32 v26, v154
	v_mov_b32_e32 v27, v155
	v_sub_u32_e64 v1, s5, 1 clamp
	s_or_b32 s56, s36, 0xc0
	s_mov_b32 s57, s37
	v_readfirstlane_b32 s0, v1
	v_lshl_add_u64 v[2:3], v[2:3], 0, s[56:57]
	v_lshlrev_b64 v[2:3], 10, v[2:3]
	v_lshl_add_u64 v[2:3], v[218:219], 0, v[2:3]
	s_max_u32 s75, s5, 4
	s_min_u32 s0, s0, 56
	s_sub_i32 s83, s0, s75
	s_mul_i32 s0, s58, 0x220000
	s_or_b32 s7, s0, s72
	s_lshl_b32 s0, s58, 3
	s_add_i32 s76, s83, 12
	s_or_b32 s82, s0, s64
	s_add_i32 s80, s83, 19
	s_cmp_lt_i32 s83, -11
	s_mov_b64 s[0:1], -1
	v_lshlrev_b32_e32 v1, 16, v4
	v_and_b32_e32 v4, 0xffff0000, v4
	v_lshlrev_b32_e32 v28, 16, v8
	v_and_b32_e32 v8, 0xffff0000, v8
	v_lshlrev_b32_e32 v29, 16, v5
	v_and_b32_e32 v5, 0xffff0000, v5
	v_lshlrev_b32_e32 v30, 16, v9
	v_and_b32_e32 v9, 0xffff0000, v9
	v_lshlrev_b32_e32 v31, 16, v6
	v_and_b32_e32 v6, 0xffff0000, v6
	v_lshlrev_b32_e32 v32, 16, v10
	v_and_b32_e32 v10, 0xffff0000, v10
	v_lshlrev_b32_e32 v33, 16, v7
	v_and_b32_e32 v7, 0xffff0000, v7
	v_lshlrev_b32_e32 v34, 16, v11
	v_and_b32_e32 v11, 0xffff0000, v11
	v_mul_f32_e32 v4, v4, v4
	v_mul_f32_e32 v8, v8, v8
	v_mul_f32_e32 v5, v5, v5
	v_mul_f32_e32 v9, v9, v9
	v_mul_f32_e32 v6, v6, v6
	v_mul_f32_e32 v10, v10, v10
	v_mul_f32_e32 v7, v7, v7
	v_mul_f32_e32 v11, v11, v11
	v_fmac_f32_e32 v4, v1, v1
	v_fmac_f32_e32 v8, v28, v28
	v_fmac_f32_e32 v5, v29, v29
	v_fmac_f32_e32 v9, v30, v30
	v_fmac_f32_e32 v6, v31, v31
	v_fmac_f32_e32 v10, v32, v32
	v_fmac_f32_e32 v7, v33, v33
	v_fmac_f32_e32 v11, v34, v34
	v_add_f32_e32 v4, v4, v8
	v_add_f32_e32 v5, v5, v9
	v_add_f32_e32 v6, v6, v10
	v_add_f32_e32 v7, v7, v11
	v_mov_b32_e32 v8, v156
	v_mov_b32_e32 v9, v157
	v_mov_b32_e32 v10, v158
	v_mov_b32_e32 v11, v159
	v_mov_b32_e32 v28, v160
	v_mov_b32_e32 v29, v161
	v_mov_b32_e32 v30, v162
	v_mov_b32_e32 v31, v163
	v_bfe_u32 v164, v226, 2, 3
	v_lshrrev_b32_e32 v165, 5, v226
	v_lshl_add_u32 v164, v164, 3, v165
	v_and_b32_e32 v166, 3, v226
	v_lshlrev_b32_e32 v166, 4, v166
	v_lshl_add_u32 v241, v164, 10, v166
	v_bfe_u32 v164, v226, 2, 2
	v_lshrrev_b32_e32 v165, 4, v226
	v_lshl_add_u32 v164, v164, 3, v165
	v_mul_u32_u24_e32 v164, 0x2200, v164
	v_add_u32_e32 v255, v164, v166
	v_readfirstlane_b32 s21, v231
	s_nop 3
	s_sub_u32 s21, s21, 0x8000
	s_lshr_b32 s84, s21, 13
	s_lshl_b32 s94, s84, 10
	s_mul_i32 s22, s58, 0x220000
	s_or_b32 s22, s22, s72
	s_lshl_b32 s22, s22, 1
	s_lshr_b32 s20, s84, 2
	s_lshl_b32 s20, s20, 12
	s_and_b32 s21, s84, 1
	s_lshl_b32 s21, s21, 11
	s_add_u32 s20, s20, s21
	s_bfe_u32 s21, s84, 0x10001
	s_lshl_b32 s21, s21, 6
	s_add_u32 s20, s20, s21
	s_add_u32 s61, s20, s22
	s_lshl_b32 s22, s58, 3
	s_or_b32 s22, s22, s64
	s_mul_i32 s22, s22, 0x88000
	s_lshr_b32 s20, s84, 2
	s_mul_i32 s20, s20, 0x44000
	s_bfe_u32 s21, s84, 0x10001
	s_mul_i32 s21, s21, 0x8800
	s_add_u32 s20, s20, s21
	s_and_b32 s21, s84, 1
	s_lshl_b32 s21, s21, 6
	s_add_u32 s20, s20, s21
	s_add_u32 s62, s20, s22
	s_lshr_b32 s20, s5, 2
	s_max_u32 s87, s5, 4
	s_sub_u32 s87, s87, 4
	s_and_b32 s86, s20, 1
	s_lshl_b32 s22, s20, 2
	s_sub_i32 s22, s22, 8
	s_max_i32 s22, s22, 0
	s_sub_i32 s22, s87, s22
	s_cmp_eq_u32 s86, 1
	s_cselect_b32 s60, s22, 0
	s_sub_i32 s93, s87, s60
	s_and_b32 s20, s20, 14
	s_cmp_eq_u32 s20, 0
	s_cselect_b32 s22, 11, 15
	s_cmp_eq_u32 s20, 14
	s_cselect_b32 s88, 12, s22
	s_mov_b32 s42, s26
	s_mov_b32 s43, s27
	s_add_u32 s20, s93, 0
	s_mov_b32 s87, 0x18000
	s_lshl_b32 s21, s20, 16
	s_add_u32 s21, s21, s61
	s_lshl_b32 s22, s20, 7
	s_add_u32 s22, s22, s62
	s_add_u32 m0, s87, s94
	s_add_u32 s84, s87, s94
	s_add_u32 s84, s84, 0x2000
	buffer_load_dwordx4 v241, s[24:27], s21 offen lds
	s_mov_b32 m0, s84
	s_nop 0
	buffer_load_dwordx4 v255, s[40:43], s22 offen lds
	s_add_u32 s20, s93, 1
	s_mov_b32 s87, 0x1c000
	s_lshl_b32 s21, s20, 16
	s_add_u32 s21, s21, s61
	s_lshl_b32 s22, s20, 7
	s_add_u32 s22, s22, s62
	s_add_u32 m0, s87, s94
	s_add_u32 s84, s87, s94
	s_add_u32 s84, s84, 0x2000
	buffer_load_dwordx4 v241, s[24:27], s21 offen lds
	s_mov_b32 m0, s84
	s_nop 0
	buffer_load_dwordx4 v255, s[40:43], s22 offen lds
	s_add_u32 s20, s93, 2
	s_mov_b32 s87, 0x20010
	s_lshl_b32 s21, s20, 16
	s_add_u32 s21, s21, s61
	s_lshl_b32 s22, s20, 7
	s_add_u32 s22, s22, s62
	s_add_u32 m0, s87, s94
	s_add_u32 s84, s87, s94
	s_add_u32 s84, s84, 0x2000
	buffer_load_dwordx4 v241, s[24:27], s21 offen lds
	s_mov_b32 m0, s84
	s_nop 0
	buffer_load_dwordx4 v255, s[40:43], s22 offen lds
	s_mov_b32 s20, 64
	s_mov_b32 s87, 0x8000
	s_lshl_b32 s21, s20, 16
	s_add_u32 s21, s21, s61
	s_lshl_b32 s22, s20, 7
	s_add_u32 s22, s22, s62
	s_add_u32 m0, s87, s94
	s_add_u32 s84, s87, s94
	s_add_u32 s84, s84, 0x2000
	buffer_load_dwordx4 v241, s[24:27], s21 offen lds
	s_mov_b32 m0, s84
	s_nop 0
	buffer_load_dwordx4 v255, s[40:43], s22 offen lds
	s_mov_b32 s20, 65
	s_mov_b32 s87, 0xc000
	s_lshl_b32 s21, s20, 16
	s_add_u32 s21, s21, s61
	s_lshl_b32 s22, s20, 7
	s_add_u32 s22, s22, s62
	s_add_u32 m0, s87, s94
	s_add_u32 s84, s87, s94
	s_add_u32 s84, s84, 0x2000
	buffer_load_dwordx4 v241, s[24:27], s21 offen lds
	s_mov_b32 m0, s84
	s_nop 0
	buffer_load_dwordx4 v255, s[40:43], s22 offen lds
	s_mov_b32 s20, 66
	s_mov_b32 s87, 0x10000
	s_lshl_b32 s21, s20, 16
	s_add_u32 s21, s21, s61
	s_lshl_b32 s22, s20, 7
	s_add_u32 s22, s22, s62
	s_add_u32 m0, s87, s94
	s_add_u32 s84, s87, s94
	s_add_u32 s84, s84, 0x2000
	buffer_load_dwordx4 v241, s[24:27], s21 offen lds
	s_mov_b32 m0, s84
	s_nop 0
	buffer_load_dwordx4 v255, s[40:43], s22 offen lds
	s_mov_b32 s20, 67
	s_mov_b32 s87, 0x14000
	s_lshl_b32 s21, s20, 16
	s_add_u32 s21, s21, s61
	s_lshl_b32 s22, s20, 7
	s_add_u32 s22, s22, s62
	s_add_u32 m0, s87, s94
	s_add_u32 s84, s87, s94
	s_add_u32 s84, s84, 0x2000
	buffer_load_dwordx4 v241, s[24:27], s21 offen lds
	s_mov_b32 m0, s84
	s_nop 0
	buffer_load_dwordx4 v255, s[40:43], s22 offen lds
	v_lshlrev_b32_e32 v35, 16, v12
	v_and_b32_e32 v12, 0xffff0000, v12
	v_lshlrev_b32_e32 v36, 16, v16
	v_and_b32_e32 v16, 0xffff0000, v16
	v_mul_f32_e32 v1, v12, v12
	v_mul_f32_e32 v12, v16, v16
	v_lshlrev_b32_e32 v37, 16, v13
	v_and_b32_e32 v13, 0xffff0000, v13
	v_lshlrev_b32_e32 v38, 16, v17
	v_and_b32_e32 v17, 0xffff0000, v17
	v_fmac_f32_e32 v1, v35, v35
	v_fmac_f32_e32 v12, v36, v36
	v_add_f32_e32 v4, v4, v5
	v_mul_f32_e32 v13, v13, v13
	v_add_f32_e32 v5, v1, v12
	v_add_f32_e32 v1, v6, v4
	v_mul_f32_e32 v6, v17, v17
	v_fmac_f32_e32 v13, v37, v37
	v_fmac_f32_e32 v6, v38, v38
	v_add_f32_e32 v2, v13, v6
	v_add_f32_e32 v2, v5, v2
	v_and_b32_e32 v5, 0xffff0000, v14
	v_add_f32_e32 v1, v7, v1
	v_lshlrev_b32_e32 v3, 16, v14
	v_and_b32_e32 v7, 0xffff0000, v18
	v_mul_f32_e32 v5, v5, v5
	v_lshlrev_b32_e32 v6, 16, v18
	v_fmac_f32_e32 v5, v3, v3
	v_mul_f32_e32 v3, v7, v7
	v_fmac_f32_e32 v3, v6, v6
	v_add_f32_e32 v3, v5, v3
	v_and_b32_e32 v5, 0xffff0000, v15
	v_add_f32_e32 v2, v3, v2
	v_lshlrev_b32_e32 v3, 16, v15
	v_and_b32_e32 v7, 0xffff0000, v19
	v_mul_f32_e32 v5, v5, v5
	v_lshlrev_b32_e32 v6, 16, v19
	v_fmac_f32_e32 v5, v3, v3
	v_mul_f32_e32 v3, v7, v7
	v_fmac_f32_e32 v3, v6, v6
	v_and_b32_e32 v6, 0xffff0000, v20
	v_add_f32_e32 v3, v5, v3
	v_lshlrev_b32_e32 v5, 16, v20
	v_and_b32_e32 v12, 0xffff0000, v24
	v_mul_f32_e32 v6, v6, v6
	v_lshlrev_b32_e32 v7, 16, v24
	v_fmac_f32_e32 v6, v5, v5
	v_mul_f32_e32 v5, v12, v12
	v_fmac_f32_e32 v5, v7, v7
	v_and_b32_e32 v7, 0xffff0000, v21
	v_add_f32_e32 v5, v6, v5
	v_lshlrev_b32_e32 v6, 16, v21
	v_and_b32_e32 v13, 0xffff0000, v25
	v_mul_f32_e32 v7, v7, v7
	v_lshlrev_b32_e32 v12, 16, v25
	v_fmac_f32_e32 v7, v6, v6
	v_mul_f32_e32 v6, v13, v13
	v_fmac_f32_e32 v6, v12, v12
	v_add_f32_e32 v6, v7, v6
	v_and_b32_e32 v7, 0xffff0000, v22
	v_add_f32_e32 v5, v5, v6
	v_lshlrev_b32_e32 v6, 16, v22
	v_and_b32_e32 v13, 0xffff0000, v26
	v_mul_f32_e32 v7, v7, v7
	v_lshlrev_b32_e32 v12, 16, v26
	v_fmac_f32_e32 v7, v6, v6
	v_mul_f32_e32 v6, v13, v13
	v_fmac_f32_e32 v6, v12, v12
	v_add_f32_e32 v6, v7, v6
	v_and_b32_e32 v7, 0xffff0000, v23
	v_add_f32_e32 v5, v6, v5
	v_lshlrev_b32_e32 v6, 16, v23
	v_and_b32_e32 v13, 0xffff0000, v27
	v_mul_f32_e32 v7, v7, v7
	v_lshlrev_b32_e32 v12, 16, v27
	v_fmac_f32_e32 v7, v6, v6
	v_mul_f32_e32 v6, v13, v13
	v_fmac_f32_e32 v6, v12, v12
	v_add_f32_e32 v6, v7, v6
	v_lshlrev_b32_e32 v7, 16, v8
	v_and_b32_e32 v8, 0xffff0000, v8
	v_and_b32_e32 v13, 0xffff0000, v28
	v_mul_f32_e32 v8, v8, v8
	v_lshlrev_b32_e32 v12, 16, v28
	v_fmac_f32_e32 v8, v7, v7
	v_mul_f32_e32 v7, v13, v13
	v_fmac_f32_e32 v7, v12, v12
	v_add_f32_e32 v7, v8, v7
	v_lshlrev_b32_e32 v8, 16, v9
	v_and_b32_e32 v9, 0xffff0000, v9
	v_and_b32_e32 v13, 0xffff0000, v29
	v_mul_f32_e32 v9, v9, v9
	v_lshlrev_b32_e32 v12, 16, v29
	v_fmac_f32_e32 v9, v8, v8
	v_mul_f32_e32 v8, v13, v13
	v_fmac_f32_e32 v8, v12, v12
	v_add_f32_e32 v8, v9, v8
	v_and_b32_e32 v9, 0xffff0000, v10
	v_add_f32_e32 v7, v7, v8
	v_lshlrev_b32_e32 v8, 16, v10
	v_and_b32_e32 v12, 0xffff0000, v30
	v_mul_f32_e32 v9, v9, v9
	v_lshlrev_b32_e32 v10, 16, v30
	v_fmac_f32_e32 v9, v8, v8
	v_mul_f32_e32 v8, v12, v12
	v_fmac_f32_e32 v8, v10, v10
	v_add_f32_e32 v8, v9, v8
	v_and_b32_e32 v9, 0xffff0000, v11
	v_add_f32_e32 v7, v8, v7
	v_lshlrev_b32_e32 v8, 16, v11
	v_and_b32_e32 v11, 0xffff0000, v31
	v_mul_f32_e32 v9, v9, v9
	v_lshlrev_b32_e32 v10, 16, v31
	v_fmac_f32_e32 v9, v8, v8
	v_mul_f32_e32 v8, v11, v11
	v_fmac_f32_e32 v8, v10, v10
	v_add_f32_e32 v8, v9, v8
	v_add_f32_e32 v2, v3, v2
	v_add_f32_e32 v5, v6, v5
	v_add_f32_e32 v7, v8, v7
	v_mov_b32_e32 v4, v1
	v_mov_b32_e32 v3, v2
	v_mov_b32_e32 v6, v5
	v_mov_b32_e32 v8, v7
	v_permlane16_swap_b32_e32 v1, v4
	v_permlane16_swap_b32_e32 v2, v3
	v_permlane16_swap_b32_e32 v5, v6
	v_permlane16_swap_b32_e32 v7, v8
	v_add_f32_e32 v1, v1, v4
	v_add_f32_e32 v2, v2, v3
	v_add_f32_e32 v5, v5, v6
	v_add_f32_e32 v7, v7, v8
	v_mov_b32_e32 v4, v1
	v_mov_b32_e32 v3, v2
	v_mov_b32_e32 v6, v5
	v_mov_b32_e32 v8, v7
	v_sub_u32_e64 v9, s5, 4 clamp
	v_permlane32_swap_b32_e32 v1, v4
	v_permlane32_swap_b32_e32 v2, v3
	v_permlane32_swap_b32_e32 v5, v6
	v_permlane32_swap_b32_e32 v7, v8
	v_readfirstlane_b32 s77, v9
	s_cbranch_scc0 .LBB0_458
	s_min_i32 s0, s80, 0
	s_sub_i32 s0, s0, s76
	s_lshl_b32 s0, s0, 5
	s_add_i32 s6, s0, 0x1000
	s_cbranch_execnz .LBB0_460
	s_branch .LBB0_459
